# nt hint: + prologue f32 weight / adaLN weight loads
# speedup vs baseline: 1.0105x; 1.0005x over previous
.LBB0_11:
	v_mov_b32_e32 v4, v3
	v_mov_b32_e32 v10, v2
	v_mov_b32_e32 v11, v5
	v_add_u32_e32 v12, 0x400, v2
	v_mov_b32_e32 v13, v5
	s_add_i32 s0, s0, 4
	v_lshlrev_b64 v[10:11], 2, v[10:11]
	v_lshlrev_b64 v[14:15], 2, v[4:5]
	v_add_u32_e32 v4, 0x400, v3
	v_lshlrev_b64 v[16:17], 2, v[12:13]
	v_cmp_eq_u32_e32 vcc, s0, v6
	v_lshl_add_u64 v[18:19], s[38:39], 0, v[10:11]
	v_lshl_add_u64 v[20:21], s[38:39], 0, v[14:15]
	v_lshl_add_u64 v[14:15], s[42:43], 0, v[14:15]
	v_lshl_add_u64 v[10:11], s[42:43], 0, v[10:11]
	v_lshlrev_b64 v[24:25], 2, v[4:5]
	v_lshl_add_u64 v[22:23], s[38:39], 0, v[16:17]
	v_lshl_add_u64 v[16:17], s[42:43], 0, v[16:17]
	s_or_b64 s[14:15], vcc, s[14:15]
	v_lshl_add_u64 v[10:11], v[10:11], 0, s[16:17]
	v_cmp_gt_u32_e32 vcc, s1, v2
	v_lshl_add_u64 v[14:15], v[14:15], 0, s[16:17]
	v_cmp_gt_u32_e64 s[4:5], s1, v3
	v_cmp_gt_u32_e64 s[6:7], s1, v12
	v_lshl_add_u64 v[12:13], s[38:39], 0, v[24:25]
	v_lshl_add_u64 v[24:25], s[42:43], 0, v[24:25]
	v_lshl_add_u64 v[16:17], v[16:17], 0, s[16:17]
	v_cndmask_b32_e64 v15, v15, v21, s[4:5]
	v_cndmask_b32_e64 v14, v14, v20, s[4:5]
	v_cndmask_b32_e32 v11, v11, v19, vcc
	v_cndmask_b32_e32 v10, v10, v18, vcc
	v_lshl_add_u64 v[18:19], v[24:25], 0, s[16:17]
	v_cmp_gt_u32_e32 vcc, s1, v4
	v_cndmask_b32_e64 v17, v17, v23, s[6:7]
	v_cndmask_b32_e64 v16, v16, v22, s[6:7]
	global_load_dword v4, v[14:15], off nt
	s_nop 0
	global_load_dword v14, v[10:11], off nt
	global_load_dword v15, v[16:17], off nt
	v_cndmask_b32_e32 v11, v19, v13, vcc
	v_cndmask_b32_e32 v10, v18, v12, vcc
	global_load_dword v16, v[10:11], off nt
	v_add_u32_e32 v9, 0xfffff000, v7
	v_add_u32_e32 v1, 0xffffe800, v7
	v_add_u32_e32 v26, 0xfffff800, v7
	v_add_u32_e32 v3, 0x800, v3
	v_add_u32_e32 v2, 0x800, v2
	s_waitcnt vmcnt(3)
	v_mul_f32_e32 v10, 0xbfb8aa3b, v4
	s_waitcnt vmcnt(2)
	v_mul_f32_e32 v11, 0xbfb8aa3b, v14
	v_fma_f32 v13, v4, s18, -v10
	v_rndne_f32_e32 v17, v10
	v_fma_f32 v18, v14, s18, -v11
	v_rndne_f32_e32 v19, v11
	s_waitcnt vmcnt(1)
	v_mul_f32_e32 v12, 0xbfb8aa3b, v15
	s_waitcnt vmcnt(0)
	v_mul_f32_e32 v20, 0xbfb8aa3b, v16
	v_fmac_f32_e32 v13, 0xb2a5705f, v4
	v_sub_f32_e32 v10, v10, v17
	v_fmac_f32_e32 v18, 0xb2a5705f, v14
	v_sub_f32_e32 v11, v11, v19
	v_fma_f32 v21, v15, s18, -v12
	v_rndne_f32_e32 v22, v12
	v_fma_f32 v23, v16, s18, -v20
	v_rndne_f32_e32 v24, v20
	v_add_f32_e32 v10, v10, v13
	v_add_f32_e32 v11, v11, v18
	v_cvt_i32_f32_e32 v17, v17
	v_cvt_i32_f32_e32 v19, v19
	v_fmac_f32_e32 v21, 0xb2a5705f, v15
	v_sub_f32_e32 v12, v12, v22
	v_fmac_f32_e32 v23, 0xb2a5705f, v16
	v_sub_f32_e32 v13, v20, v24
	v_exp_f32_e32 v10, v10
	v_exp_f32_e32 v11, v11
	v_add_f32_e32 v12, v12, v21
	v_add_f32_e32 v13, v13, v23
	v_cvt_i32_f32_e32 v22, v22
	v_cvt_i32_f32_e32 v18, v24
	v_exp_f32_e32 v12, v12
	v_exp_f32_e32 v13, v13
	v_ldexp_f32 v10, v10, v17
	v_ldexp_f32 v11, v11, v19
	v_cmp_nlt_f32_e32 vcc, s19, v14
	v_cmp_nlt_f32_e64 s[6:7], s19, v4
	v_cmp_ngt_f32_e64 s[8:9], s22, v4
	v_cndmask_b32_e32 v17, 0, v11, vcc
	v_cndmask_b32_e64 v10, 0, v10, s[6:7]
	v_cmp_ngt_f32_e32 vcc, s22, v14
	v_ldexp_f32 v12, v12, v22
	v_cmp_nlt_f32_e64 s[4:5], s19, v15
	v_ldexp_f32 v13, v13, v18
	v_cmp_nlt_f32_e64 s[6:7], s19, v16
	v_cndmask_b32_e64 v11, v8, v10, s[8:9]
	v_cndmask_b32_e32 v10, v8, v17, vcc
	v_cndmask_b32_e64 v12, 0, v12, s[4:5]
	v_cmp_ngt_f32_e64 s[4:5], s22, v15
	v_cndmask_b32_e64 v13, 0, v13, s[6:7]
	v_cmp_ngt_f32_e32 vcc, s22, v16
	v_pk_add_f32 v[10:11], v[10:11], 1.0 op_sel_hi:[1,0]
	v_cndmask_b32_e64 v12, v8, v12, s[4:5]
	v_cndmask_b32_e32 v13, v8, v13, vcc
	v_div_scale_f32 v17, s[4:5], v11, v11, v4
	v_div_scale_f32 v19, s[4:5], v10, v10, v14
	v_pk_add_f32 v[12:13], v[12:13], 1.0 op_sel_hi:[1,0]
	v_rcp_f32_e32 v21, v17
	v_rcp_f32_e32 v22, v19
	v_div_scale_f32 v23, s[6:7], v13, v13, v16
	v_div_scale_f32 v25, s[8:9], v12, v12, v15
	v_rcp_f32_e32 v28, v23
	v_rcp_f32_e32 v29, v25
	v_fma_f32 v30, -v17, v21, 1.0
	v_div_scale_f32 v18, vcc, v4, v11, v4
	v_fma_f32 v31, -v19, v22, 1.0
	v_fmac_f32_e32 v21, v30, v21
	v_div_scale_f32 v20, s[4:5], v14, v10, v14
	v_fmac_f32_e32 v22, v31, v22
	v_fma_f32 v30, -v23, v28, 1.0
	v_mul_f32_e32 v32, v18, v21
	v_div_scale_f32 v24, s[6:7], v16, v13, v16
	v_fma_f32 v31, -v25, v29, 1.0
	v_mul_f32_e32 v33, v20, v22
	v_fmac_f32_e32 v28, v30, v28
	v_fma_f32 v30, -v17, v32, v18
	v_div_scale_f32 v27, s[8:9], v15, v12, v15
	v_fmac_f32_e32 v29, v31, v29
	v_fma_f32 v31, -v19, v33, v20
	v_mul_f32_e32 v34, v24, v28
	v_fmac_f32_e32 v32, v30, v21
	v_mul_f32_e32 v35, v27, v29
	v_fmac_f32_e32 v33, v31, v22
	v_fma_f32 v30, -v23, v34, v24
	v_fma_f32 v17, -v17, v32, v18
	v_fma_f32 v31, -v25, v35, v27
	v_fma_f32 v18, -v19, v33, v20
	v_fmac_f32_e32 v34, v30, v28
	v_div_fmas_f32 v17, v17, v21, v32
	s_mov_b64 vcc, s[4:5]
	v_fmac_f32_e32 v35, v31, v29
	v_fma_f32 v19, -v23, v34, v24
	v_div_fixup_f32 v4, v17, v11, v4
	v_div_fmas_f32 v11, v18, v22, v33
	s_mov_b64 vcc, s[6:7]
	v_fma_f32 v20, -v25, v35, v27
	v_div_fixup_f32 v10, v11, v10, v14
	ds_write_b32 v9, v4
	v_div_fmas_f32 v4, v19, v28, v34
	s_mov_b64 vcc, s[8:9]
	ds_write_b32 v1, v10
	v_div_fixup_f32 v1, v4, v13, v16
	v_div_fmas_f32 v4, v20, v29, v35
	v_div_fixup_f32 v4, v4, v12, v15
	ds_write_b32 v7, v1
	v_add_u32_e32 v7, 0x2000, v7
	ds_write_b32 v26, v4
	s_andn2_b64 exec, exec, s[14:15]
	s_cbranch_execnz .LBB0_11
	s_or_b64 exec, exec, s[14:15]
	v_lshlrev_b32_e32 v4, 9, v6
	s_or_b64 exec, exec, s[12:13]
	v_cmp_eq_u32_e64 s[0:1], 2, 0
	s_and_saveexec_b64 s[6:7], s[0:1]
	s_cbranch_execnz .LBB0_15

.LBB0_15:
	v_mov_b32_e32 v7, 0
	v_mov_b32_e32 v6, v3
	v_lshlrev_b64 v[8:9], 2, v[6:7]
	s_movk_i32 s0, 0x8000
	s_movk_i32 s4, 0x2000
	v_lshl_add_u64 v[10:11], s[38:39], 0, v[8:9]
	v_lshl_add_u64 v[8:9], s[42:43], 0, v[8:9]
	s_mov_b32 s1, -1
	v_lshl_add_u64 v[8:9], v[8:9], 0, s[0:1]
	v_cmp_gt_u32_e32 vcc, s4, v3
	v_mov_b32_e32 v3, v7
	v_lshlrev_b64 v[6:7], 2, v[2:3]
	v_cndmask_b32_e32 v9, v9, v11, vcc
	v_cndmask_b32_e32 v8, v8, v10, vcc
	global_load_dword v1, v[8:9], off nt
	v_lshl_add_u64 v[8:9], s[38:39], 0, v[6:7]
	v_lshl_add_u64 v[6:7], s[42:43], 0, v[6:7]
	v_lshl_add_u64 v[6:7], v[6:7], 0, s[0:1]
	v_cmp_gt_u32_e32 vcc, s4, v2
	s_mov_b32 s0, 0xbfb8aa3b
	s_mov_b32 s1, 0x42ce8ed0
	v_cndmask_b32_e32 v3, v7, v9, vcc
	v_cndmask_b32_e32 v2, v6, v8, vcc
	global_load_dword v5, v[2:3], off nt
	v_or_b32_e32 v2, v0, v4
	v_lshl_add_u32 v6, v2, 2, 0
	s_mov_b32 s4, 0xc2b17218
	v_mov_b32_e32 v4, 0x7f800000
	s_waitcnt vmcnt(1)
	v_mul_f32_e32 v2, 0xbfb8aa3b, v1
	v_fma_f32 v3, v1, s0, -v2
	v_rndne_f32_e32 v7, v2
	v_fmac_f32_e32 v3, 0xb2a5705f, v1
	v_sub_f32_e32 v2, v2, v7
	v_add_f32_e32 v2, v2, v3
	v_cvt_i32_f32_e32 v7, v7
	v_exp_f32_e32 v2, v2
	v_cmp_nlt_f32_e32 vcc, s1, v1
	s_waitcnt vmcnt(0)
	v_mul_f32_e32 v3, 0xbfb8aa3b, v5
	v_fma_f32 v8, v5, s0, -v3
	v_rndne_f32_e32 v9, v3
	v_fmac_f32_e32 v8, 0xb2a5705f, v5
	v_sub_f32_e32 v3, v3, v9
	v_add_f32_e32 v3, v3, v8
	v_cvt_i32_f32_e32 v9, v9
	v_exp_f32_e32 v8, v3
	v_ldexp_f32 v2, v2, v7
	v_cndmask_b32_e32 v2, 0, v2, vcc
	v_cmp_ngt_f32_e32 vcc, s4, v1
	s_nop 1
	v_cndmask_b32_e32 v3, v4, v2, vcc
	v_ldexp_f32 v2, v8, v9
	v_cmp_nlt_f32_e32 vcc, s1, v5
	s_nop 1
	v_cndmask_b32_e32 v2, 0, v2, vcc
	v_cmp_ngt_f32_e32 vcc, s4, v5
	s_nop 1
	v_cndmask_b32_e32 v2, v4, v2, vcc
	v_pk_add_f32 v[2:3], v[2:3], 1.0 op_sel_hi:[1,0]
	s_nop 0
	v_div_scale_f32 v4, s[0:1], v3, v3, v1
	v_div_scale_f32 v8, s[0:1], v2, v2, v5
	v_rcp_f32_e32 v9, v4
	v_rcp_f32_e32 v10, v8
	v_div_scale_f32 v7, vcc, v1, v3, v1
	v_fma_f32 v12, -v4, v9, 1.0
	v_fma_f32 v13, -v8, v10, 1.0
	v_fmac_f32_e32 v9, v12, v9
	v_div_scale_f32 v11, s[4:5], v5, v2, v5
	v_fmac_f32_e32 v10, v13, v10
	v_mul_f32_e32 v12, v7, v9
	v_mul_f32_e32 v13, v11, v10
	v_fma_f32 v14, -v4, v12, v7
	v_fma_f32 v15, -v8, v13, v11
	v_fmac_f32_e32 v12, v14, v9
	v_fmac_f32_e32 v13, v15, v10
	v_fma_f32 v4, -v4, v12, v7
	v_fma_f32 v7, -v8, v13, v11
	v_div_fmas_f32 v4, v4, v9, v12
	s_mov_b64 vcc, s[4:5]
	v_div_fixup_f32 v1, v4, v3, v1
	v_div_fmas_f32 v3, v7, v10, v13
	v_div_fixup_f32 v2, v3, v2, v5
	v_add_u32_e32 v3, 0x12000, v6
	ds_write2st64_b32 v3, v2, v1 offset1:8
	s_or_b64 exec, exec, s[6:7]
	v_cmp_ne_u32_e64 s[0:1], 24, 24
	s_and_saveexec_b64 s[4:5], s[0:1]
	s_cbranch_execz .LBB0_18

.LBB0_17:
	v_cmp_gt_u32_e32 vcc, s0, v1
	s_nop 1
	v_cndmask_b32_e32 v9, v3, v5, vcc
	v_cndmask_b32_e32 v8, v2, v4, vcc
	global_load_dword v8, v[8:9], off nt
	v_add_u32_e32 v9, 0x200, v1
	v_cmp_lt_u32_e32 vcc, s14, v1
	v_mov_b32_e32 v1, v9
	s_or_b64 s[6:7], vcc, s[6:7]
	v_lshl_add_u64 v[2:3], v[2:3], 0, s[8:9]
	v_lshl_add_u64 v[4:5], v[4:5], 0, s[8:9]
	s_waitcnt vmcnt(0)
	v_mul_f32_e32 v9, 0xbfb8aa3b, v8
	v_fma_f32 v10, v8, s1, -v9
	v_rndne_f32_e32 v11, v9
	v_fmac_f32_e32 v10, 0xb2a5705f, v8
	v_sub_f32_e32 v9, v9, v11
	v_add_f32_e32 v9, v9, v10
	v_cvt_i32_f32_e32 v11, v11
	v_exp_f32_e32 v9, v9
	v_cmp_nlt_f32_e32 vcc, s12, v8
	v_ldexp_f32 v9, v9, v11
	s_nop 0
	v_cndmask_b32_e32 v9, 0, v9, vcc
	v_cmp_ngt_f32_e32 vcc, s13, v8
	s_nop 1
	v_cndmask_b32_e32 v9, v7, v9, vcc
	v_add_f32_e32 v9, 1.0, v9
	v_div_scale_f32 v10, s[16:17], v9, v9, v8
	v_rcp_f32_e32 v11, v10
	v_div_scale_f32 v12, vcc, v8, v9, v8
	v_fma_f32 v13, -v10, v11, 1.0
	v_fmac_f32_e32 v11, v13, v11
	v_mul_f32_e32 v13, v12, v11
	v_fma_f32 v14, -v10, v13, v12
	v_fmac_f32_e32 v13, v14, v11
	v_fma_f32 v10, -v10, v13, v12
	v_div_fmas_f32 v10, v10, v11, v13
	v_div_fixup_f32 v8, v10, v9, v8
	ds_write_b32 v6, v8
	v_add_u32_e32 v6, 0x800, v6
	s_andn2_b64 exec, exec, s[6:7]
	s_cbranch_execnz .LBB0_17

.LBB0_22:
	v_lshl_add_u64 v[62:63], v[34:35], 0, s[14:15]
	v_lshl_add_u64 v[66:67], v[36:37], 0, s[14:15]
	v_lshl_add_u64 v[70:71], v[32:33], 0, s[14:15]
	v_lshl_add_u64 v[74:75], v[30:31], 0, s[14:15]
	v_lshl_add_u64 v[78:79], v[28:29], 0, s[14:15]
	v_lshl_add_u64 v[82:83], v[26:27], 0, s[14:15]
	v_lshl_add_u64 v[86:87], v[24:25], 0, s[14:15]
	v_lshl_add_u64 v[90:91], v[22:23], 0, s[14:15]
	ds_read2_b32 v[48:49], v59 offset1:8
	ds_read2_b32 v[94:95], v59 offset0:16 offset1:24
	ds_read2_b32 v[96:97], v59 offset0:32 offset1:40
	ds_read2_b32 v[98:99], v59 offset0:48 offset1:56
	global_load_dwordx4 v[62:65], v[62:63], off nt
	s_nop 0
	global_load_dwordx4 v[66:69], v[66:67], off nt
	s_nop 0
	global_load_dwordx4 v[70:73], v[70:71], off nt
	s_nop 0
	global_load_dwordx4 v[74:77], v[74:75], off nt
	s_nop 0
	global_load_dwordx4 v[78:81], v[78:79], off nt
	s_nop 0
	global_load_dwordx4 v[82:85], v[82:83], off nt
	s_nop 0
	global_load_dwordx4 v[86:89], v[86:87], off nt
	s_nop 0
	global_load_dwordx4 v[90:93], v[90:91], off nt
	v_add_u32_e32 v61, 0x4000, v59
	v_add_u32_e32 v114, 0x8000, v59
	ds_read2_b32 v[100:101], v61 offset1:8
	ds_read2_b32 v[102:103], v114 offset1:8
	ds_read2_b32 v[104:105], v61 offset0:16 offset1:24
	ds_read2_b32 v[106:107], v114 offset0:16 offset1:24
	ds_read2_b32 v[108:109], v61 offset0:32 offset1:40
	ds_read2_b32 v[110:111], v114 offset0:32 offset1:40
	ds_read2_b32 v[112:113], v61 offset0:48 offset1:56
	ds_read2_b32 v[114:115], v114 offset0:48 offset1:56
	s_waitcnt lgkmcnt(11)
	v_mov_b32_e32 v116, v49
	s_waitcnt lgkmcnt(7)
	v_mov_b32_e32 v124, v101
	s_waitcnt lgkmcnt(6)
	v_mov_b32_e32 v126, v103
	v_mov_b32_e32 v118, v95
	s_waitcnt lgkmcnt(5)
	v_mov_b32_e32 v128, v105
	s_waitcnt lgkmcnt(4)
	v_mov_b32_e32 v130, v107
	v_mov_b32_e32 v120, v97
	s_waitcnt lgkmcnt(3)
	v_mov_b32_e32 v132, v109
	s_waitcnt lgkmcnt(2)
	v_mov_b32_e32 v134, v111
	v_add_u32_e32 v60, 64, v60
	v_cmp_ge_u32_e64 s[6:7], v60, v51
	v_mov_b32_e32 v122, v99
	s_waitcnt lgkmcnt(1)
	v_mov_b32_e32 v136, v113
	s_waitcnt lgkmcnt(0)
	v_mov_b32_e32 v138, v115
	v_lshl_add_u64 v[22:23], v[22:23], 0, s[8:9]
	v_lshl_add_u64 v[24:25], v[24:25], 0, s[8:9]
	v_lshl_add_u64 v[26:27], v[26:27], 0, s[8:9]
	v_lshl_add_u64 v[28:29], v[28:29], 0, s[8:9]
	v_lshl_add_u64 v[30:31], v[30:31], 0, s[8:9]
	v_lshl_add_u64 v[32:33], v[32:33], 0, s[8:9]
	v_lshl_add_u64 v[34:35], v[34:35], 0, s[8:9]
	v_lshl_add_u64 v[36:37], v[36:37], 0, s[8:9]
	v_add_u32_e32 v59, 0x100, v59
	s_or_b64 s[16:17], s[6:7], s[16:17]
	s_waitcnt vmcnt(7)
	v_pk_fma_f32 v[44:45], v[62:63], v[48:49], v[44:45] op_sel_hi:[1,0,1]
	v_pk_fma_f32 v[40:41], v[64:65], v[48:49], v[40:41] op_sel_hi:[1,0,1]
	v_pk_fma_f32 v[46:47], v[62:63], v[100:101], v[46:47] op_sel_hi:[1,0,1]
	v_pk_fma_f32 v[38:39], v[64:65], v[100:101], v[38:39] op_sel_hi:[1,0,1]
	v_pk_fma_f32 v[42:43], v[62:63], v[102:103], v[42:43] op_sel_hi:[1,0,1]
	v_pk_fma_f32 v[20:21], v[64:65], v[102:103], v[20:21] op_sel_hi:[1,0,1]
	s_waitcnt vmcnt(6)
	v_pk_fma_f32 v[40:41], v[68:69], v[116:117], v[40:41] op_sel_hi:[1,0,1]
	v_pk_fma_f32 v[44:45], v[66:67], v[116:117], v[44:45] op_sel_hi:[1,0,1]
	v_pk_fma_f32 v[38:39], v[68:69], v[124:125], v[38:39] op_sel_hi:[1,0,1]
	v_pk_fma_f32 v[46:47], v[66:67], v[124:125], v[46:47] op_sel_hi:[1,0,1]
	v_pk_fma_f32 v[20:21], v[68:69], v[126:127], v[20:21] op_sel_hi:[1,0,1]
	v_pk_fma_f32 v[42:43], v[66:67], v[126:127], v[42:43] op_sel_hi:[1,0,1]
	s_waitcnt vmcnt(5)
	v_pk_fma_f32 v[44:45], v[70:71], v[94:95], v[44:45] op_sel_hi:[1,0,1]
	v_pk_fma_f32 v[40:41], v[72:73], v[94:95], v[40:41] op_sel_hi:[1,0,1]
	v_pk_fma_f32 v[46:47], v[70:71], v[104:105], v[46:47] op_sel_hi:[1,0,1]
	v_pk_fma_f32 v[38:39], v[72:73], v[104:105], v[38:39] op_sel_hi:[1,0,1]
	v_pk_fma_f32 v[42:43], v[70:71], v[106:107], v[42:43] op_sel_hi:[1,0,1]
	v_pk_fma_f32 v[20:21], v[72:73], v[106:107], v[20:21] op_sel_hi:[1,0,1]
	s_waitcnt vmcnt(4)
	v_pk_fma_f32 v[40:41], v[76:77], v[118:119], v[40:41] op_sel_hi:[1,0,1]
	v_pk_fma_f32 v[44:45], v[74:75], v[118:119], v[44:45] op_sel_hi:[1,0,1]
	v_pk_fma_f32 v[38:39], v[76:77], v[128:129], v[38:39] op_sel_hi:[1,0,1]
	v_pk_fma_f32 v[46:47], v[74:75], v[128:129], v[46:47] op_sel_hi:[1,0,1]
	v_pk_fma_f32 v[20:21], v[76:77], v[130:131], v[20:21] op_sel_hi:[1,0,1]
	v_pk_fma_f32 v[42:43], v[74:75], v[130:131], v[42:43] op_sel_hi:[1,0,1]
	s_waitcnt vmcnt(3)
	v_pk_fma_f32 v[44:45], v[78:79], v[96:97], v[44:45] op_sel_hi:[1,0,1]
	v_pk_fma_f32 v[40:41], v[80:81], v[96:97], v[40:41] op_sel_hi:[1,0,1]
	v_pk_fma_f32 v[46:47], v[78:79], v[108:109], v[46:47] op_sel_hi:[1,0,1]
	v_pk_fma_f32 v[38:39], v[80:81], v[108:109], v[38:39] op_sel_hi:[1,0,1]
	v_pk_fma_f32 v[42:43], v[78:79], v[110:111], v[42:43] op_sel_hi:[1,0,1]
	v_pk_fma_f32 v[20:21], v[80:81], v[110:111], v[20:21] op_sel_hi:[1,0,1]
	s_waitcnt vmcnt(2)
	v_pk_fma_f32 v[40:41], v[84:85], v[120:121], v[40:41] op_sel_hi:[1,0,1]
	v_pk_fma_f32 v[44:45], v[82:83], v[120:121], v[44:45] op_sel_hi:[1,0,1]
	v_pk_fma_f32 v[38:39], v[84:85], v[132:133], v[38:39] op_sel_hi:[1,0,1]
	v_pk_fma_f32 v[46:47], v[82:83], v[132:133], v[46:47] op_sel_hi:[1,0,1]
	v_pk_fma_f32 v[20:21], v[84:85], v[134:135], v[20:21] op_sel_hi:[1,0,1]
	v_pk_fma_f32 v[42:43], v[82:83], v[134:135], v[42:43] op_sel_hi:[1,0,1]
	s_waitcnt vmcnt(1)
	v_pk_fma_f32 v[44:45], v[86:87], v[98:99], v[44:45] op_sel_hi:[1,0,1]
	v_pk_fma_f32 v[40:41], v[88:89], v[98:99], v[40:41] op_sel_hi:[1,0,1]
	v_pk_fma_f32 v[46:47], v[86:87], v[112:113], v[46:47] op_sel_hi:[1,0,1]
	v_pk_fma_f32 v[38:39], v[88:89], v[112:113], v[38:39] op_sel_hi:[1,0,1]
	v_pk_fma_f32 v[42:43], v[86:87], v[114:115], v[42:43] op_sel_hi:[1,0,1]
	v_pk_fma_f32 v[20:21], v[88:89], v[114:115], v[20:21] op_sel_hi:[1,0,1]
	s_waitcnt vmcnt(0)
	v_pk_fma_f32 v[40:41], v[92:93], v[122:123], v[40:41] op_sel_hi:[1,0,1]
	v_pk_fma_f32 v[44:45], v[90:91], v[122:123], v[44:45] op_sel_hi:[1,0,1]
	v_pk_fma_f32 v[38:39], v[92:93], v[136:137], v[38:39] op_sel_hi:[1,0,1]
	v_pk_fma_f32 v[46:47], v[90:91], v[136:137], v[46:47] op_sel_hi:[1,0,1]
	v_pk_fma_f32 v[20:21], v[92:93], v[138:139], v[20:21] op_sel_hi:[1,0,1]
	v_pk_fma_f32 v[42:43], v[90:91], v[138:139], v[42:43] op_sel_hi:[1,0,1]
	s_andn2_b64 exec, exec, s[16:17]
	s_cbranch_execnz .LBB0_22
	s_or_b64 exec, exec, s[16:17]
	ds_bpermute_b32 v22, v1, v44
	ds_bpermute_b32 v23, v1, v45
	ds_bpermute_b32 v24, v1, v46
	ds_bpermute_b32 v26, v1, v42
	ds_bpermute_b32 v25, v1, v47
	ds_bpermute_b32 v27, v1, v43
	ds_bpermute_b32 v28, v1, v40
	ds_bpermute_b32 v30, v1, v38
	s_waitcnt lgkmcnt(6)
	v_pk_add_f32 v[22:23], v[44:45], v[22:23]
	ds_bpermute_b32 v34, v1, v20
	ds_bpermute_b32 v29, v1, v41
	ds_bpermute_b32 v31, v1, v39
	ds_bpermute_b32 v35, v1, v21
	ds_bpermute_b32 v32, v3, v22
	ds_bpermute_b32 v33, v3, v23
	s_waitcnt lgkmcnt(9)
	v_pk_add_f32 v[24:25], v[46:47], v[24:25]
	s_waitcnt lgkmcnt(8)
	v_pk_add_f32 v[26:27], v[42:43], v[26:27]
	s_waitcnt lgkmcnt(4)
	v_pk_add_f32 v[28:29], v[40:41], v[28:29]
	s_waitcnt lgkmcnt(3)
	v_pk_add_f32 v[38:39], v[38:39], v[30:31]
	s_waitcnt lgkmcnt(2)
	v_pk_add_f32 v[34:35], v[20:21], v[34:35]
	s_waitcnt lgkmcnt(0)
	v_pk_add_f32 v[22:23], v[22:23], v[32:33]
	ds_bpermute_b32 v32, v3, v24
	ds_bpermute_b32 v33, v3, v25
	ds_bpermute_b32 v36, v3, v26
	ds_bpermute_b32 v37, v3, v27
	ds_bpermute_b32 v40, v3, v28
	ds_bpermute_b32 v41, v3, v29
	ds_bpermute_b32 v42, v3, v38
	ds_bpermute_b32 v43, v3, v39
	ds_bpermute_b32 v44, v3, v34
	ds_bpermute_b32 v45, v3, v35
	s_waitcnt lgkmcnt(8)
	v_pk_add_f32 v[24:25], v[24:25], v[32:33]
	s_waitcnt lgkmcnt(6)
	v_pk_add_f32 v[30:31], v[26:27], v[36:37]
	s_waitcnt lgkmcnt(4)
	v_pk_add_f32 v[20:21], v[28:29], v[40:41]
	s_waitcnt lgkmcnt(2)
	v_pk_add_f32 v[28:29], v[38:39], v[42:43]
	s_waitcnt lgkmcnt(0)
	v_pk_add_f32 v[36:37], v[34:35], v[44:45]
	ds_bpermute_b32 v26, v50, v22
	ds_bpermute_b32 v32, v50, v24
	ds_bpermute_b32 v38, v50, v30
	ds_bpermute_b32 v27, v50, v23
	ds_bpermute_b32 v33, v50, v25
	ds_bpermute_b32 v39, v50, v31
	ds_bpermute_b32 v34, v50, v20
	ds_bpermute_b32 v40, v50, v28
	ds_bpermute_b32 v42, v50, v36
	ds_bpermute_b32 v35, v50, v21
	ds_bpermute_b32 v41, v50, v29
	ds_bpermute_b32 v43, v50, v37
	s_and_saveexec_b64 s[6:7], vcc
	s_cbranch_execz .LBB0_25
	s_waitcnt lgkmcnt(0)
	v_pk_add_f32 v[44:45], v[36:37], v[42:43]
	v_pk_add_f32 v[42:43], v[30:31], v[38:39]
	v_pk_add_f32 v[30:31], v[28:29], v[40:41]
	v_pk_add_f32 v[28:29], v[24:25], v[32:33]
	v_pk_add_f32 v[24:25], v[20:21], v[34:35]
	v_pk_add_f32 v[22:23], v[22:23], v[26:27]
	ds_write_b128 v56, v[22:25]
	ds_write_b128 v52, v[28:31] offset:128
	ds_write_b128 v52, v[42:45] offset:256
.LBB0_25:
	s_or_b64 exec, exec, s[6:7]
	s_waitcnt lgkmcnt(0)
	s_barrier
	s_and_saveexec_b64 s[6:7], s[4:5]
	s_cbranch_execz .LBB0_20
	s_mul_i32 s13, s18, 0x3000
	s_add_i32 s13, s13, s12
	v_or_b32_e32 v20, s13, v53
	v_ashrrev_i32_e32 v21, 31, v20
	v_lshl_add_u64 v[20:21], v[20:21], 2, s[48:49]
	global_load_dword v30, v[20:21], off nt
	ds_read2_b32 v[20:21], v57 offset1:96
	v_add_u32_e32 v24, 0x200, v57
	v_add_u32_e32 v26, 0x400, v57
	v_add_u32_e32 v28, 0x800, v57
	ds_read2_b32 v[24:25], v24 offset0:64 offset1:160
	ds_read2_b32 v[26:27], v26 offset0:128 offset1:224
	ds_read2_b32 v[28:29], v28 offset0:64 offset1:160
	s_waitcnt lgkmcnt(3)
	v_add_f32_e32 v20, 0, v20
	v_add_f32_e32 v20, v20, v21
	s_waitcnt lgkmcnt(2)
	v_add_f32_e32 v20, v20, v24
	v_mad_u64_u32 v[22:23], s[14:15], s18, 3, v[2:3]
	v_add_f32_e32 v20, v20, v25
	v_mul_lo_u32 v22, v22, s0
	s_waitcnt lgkmcnt(1)
	v_add_f32_e32 v20, v20, v26
	v_add_u32_e32 v22, s12, v22
	v_add_f32_e32 v20, v20, v27
	v_or_b32_e32 v22, v22, v53
	s_waitcnt lgkmcnt(0)
	v_add_f32_e32 v20, v20, v28
	v_ashrrev_i32_e32 v23, 31, v22
	v_add_f32_e32 v20, v20, v29
	s_waitcnt vmcnt(0)
	v_add_f32_e32 v24, v20, v30
	v_lshl_add_u64 v[20:21], v[22:23], 2, s[20:21]
	global_store_dword v[20:21], v24, off
	s_branch .LBB0_20

.LBB0_31:
	s_cmpk_gt_i32 s0, 0x45ff
	s_mov_b64 s[4:5], -1
	s_cbranch_scc0 .LBB0_108
	s_cmpk_gt_u32 s0, 0x4bff
	s_cbranch_scc0 .LBB0_100
	s_add_i32 s4, s0, 0xffffb400
	s_and_b32 s6, s18, 0xfe0
	s_lshr_b32 s4, s4, 1
	v_or_b32_e32 v2, s6, v1
	s_and_b32 s7, s4, 0x7fffffc0
	v_lshlrev_b32_e32 v2, 2, v2
	v_lshl_add_u64 v[10:11], s[62:63], 0, v[2:3]
	v_or_b32_e32 v2, s7, v14
	v_lshlrev_b64 v[12:13], 14, v[2:3]
	v_lshl_add_u64 v[12:13], v[10:11], 0, v[12:13]
	global_load_dword v12, v[12:13], off nt
	v_cndmask_b32_e64 v76, 0, 1, s[12:13]
	v_mov_b32_e32 v13, 1.0
	v_cmp_ne_u32_e64 s[4:5], 1, v76
	s_andn2_b64 vcc, exec, s[12:13]
	v_mov_b32_e32 v77, 1.0
	s_cbranch_vccnz .LBB0_35
	v_lshl_add_u64 v[76:77], v[2:3], 2, s[58:59]
	global_load_dword v77, v[76:77], off nt
.LBB0_35:
	v_or_b32_e32 v2, s7, v17
	v_lshlrev_b64 v[78:79], 14, v[2:3]
	v_lshl_add_u64 v[78:79], v[10:11], 0, v[78:79]
	global_load_dword v76, v[78:79], off nt
	s_waitcnt vmcnt(1)
	v_mul_f32_e32 v2, v12, v77
	v_add_u32_e32 v12, v15, v16
	ds_write_b32 v12, v2
	s_and_b64 vcc, exec, s[4:5]
	v_add_u32_e32 v12, s7, v14
	s_cbranch_vccnz .LBB0_37
	v_mov_b32_e32 v13, v3
	v_lshl_add_u64 v[78:79], v[12:13], 2, s[58:59]
	global_load_dword v13, v[78:79], off offset:8 nt
.LBB0_37:
	v_or_b32_e32 v2, s7, v19
	v_lshlrev_b64 v[78:79], 14, v[2:3]
	v_lshl_add_u64 v[78:79], v[10:11], 0, v[78:79]
	global_load_dword v77, v[78:79], off nt
	s_waitcnt vmcnt(1)
	v_mul_f32_e32 v2, v76, v13
	v_add_u32_e32 v13, v15, v18
	ds_write_b32 v13, v2
	v_mov_b32_e32 v76, 1.0
	s_and_b64 vcc, exec, s[4:5]
	v_mov_b32_e32 v13, 1.0
	s_cbranch_vccnz .LBB0_39
	v_mov_b32_e32 v13, v3
	v_lshl_add_u64 v[78:79], v[12:13], 2, s[58:59]
	global_load_dword v13, v[78:79], off offset:16 nt
.LBB0_39:
	v_or_b32_e32 v2, s7, v21
	v_lshlrev_b64 v[78:79], 14, v[2:3]
	v_lshl_add_u64 v[78:79], v[10:11], 0, v[78:79]
	global_load_dword v78, v[78:79], off nt
	s_waitcnt vmcnt(1)
	v_mul_f32_e32 v2, v77, v13
	v_add_u32_e32 v13, v15, v20
	s_and_b64 vcc, exec, s[4:5]
	ds_write_b32 v13, v2
	s_cbranch_vccnz .LBB0_41
	v_mov_b32_e32 v13, v3
	v_lshl_add_u64 v[76:77], v[12:13], 2, s[58:59]
	global_load_dword v76, v[76:77], off offset:24 nt
.LBB0_41:
	v_or_b32_e32 v2, s7, v23
	v_lshlrev_b64 v[80:81], 14, v[2:3]
	v_lshl_add_u64 v[80:81], v[10:11], 0, v[80:81]
	global_load_dword v77, v[80:81], off nt
	s_waitcnt vmcnt(1)
	v_mul_f32_e32 v2, v78, v76
	v_add_u32_e32 v13, v15, v22
	ds_write_b32 v13, v2
	v_mov_b32_e32 v76, 1.0
	s_and_b64 vcc, exec, s[4:5]
	v_mov_b32_e32 v13, 1.0
	s_cbranch_vccnz .LBB0_43
	v_mov_b32_e32 v13, v3
	v_lshl_add_u64 v[78:79], v[12:13], 2, s[58:59]
	global_load_dword v13, v[78:79], off offset:32 nt
.LBB0_43:
	v_or_b32_e32 v2, s7, v25
	v_lshlrev_b64 v[78:79], 14, v[2:3]
	v_lshl_add_u64 v[78:79], v[10:11], 0, v[78:79]
	global_load_dword v78, v[78:79], off nt
	s_waitcnt vmcnt(1)
	v_mul_f32_e32 v2, v77, v13
	v_add_u32_e32 v13, v15, v24
	s_and_b64 vcc, exec, s[4:5]
	ds_write_b32 v13, v2
	s_cbranch_vccnz .LBB0_45
	v_mov_b32_e32 v13, v3
	v_lshl_add_u64 v[76:77], v[12:13], 2, s[58:59]
	global_load_dword v76, v[76:77], off offset:40 nt
.LBB0_45:
	v_or_b32_e32 v2, s7, v27
	v_lshlrev_b64 v[80:81], 14, v[2:3]
	v_lshl_add_u64 v[80:81], v[10:11], 0, v[80:81]
	global_load_dword v77, v[80:81], off nt
	s_waitcnt vmcnt(1)
	v_mul_f32_e32 v2, v78, v76
	v_add_u32_e32 v13, v15, v26
	ds_write_b32 v13, v2
	v_mov_b32_e32 v76, 1.0
	s_and_b64 vcc, exec, s[4:5]
	v_mov_b32_e32 v13, 1.0
	s_cbranch_vccnz .LBB0_47
	v_mov_b32_e32 v13, v3
	v_lshl_add_u64 v[78:79], v[12:13], 2, s[58:59]
	global_load_dword v13, v[78:79], off offset:48 nt
.LBB0_47:
	v_or_b32_e32 v2, s7, v29
	v_lshlrev_b64 v[78:79], 14, v[2:3]
	v_lshl_add_u64 v[78:79], v[10:11], 0, v[78:79]
	global_load_dword v78, v[78:79], off nt
	s_waitcnt vmcnt(1)
	v_mul_f32_e32 v2, v77, v13
	v_add_u32_e32 v13, v15, v28
	s_and_b64 vcc, exec, s[4:5]
	ds_write_b32 v13, v2
	s_cbranch_vccnz .LBB0_49
	v_mov_b32_e32 v13, v3
	v_lshl_add_u64 v[76:77], v[12:13], 2, s[58:59]
	global_load_dword v76, v[76:77], off offset:56 nt
.LBB0_49:
	v_or_b32_e32 v2, s7, v31
	v_lshlrev_b64 v[80:81], 14, v[2:3]
	v_lshl_add_u64 v[80:81], v[10:11], 0, v[80:81]
	global_load_dword v77, v[80:81], off nt
	s_waitcnt vmcnt(1)
	v_mul_f32_e32 v2, v78, v76
	v_add_u32_e32 v13, v15, v30
	ds_write_b32 v13, v2
	v_mov_b32_e32 v76, 1.0
	s_and_b64 vcc, exec, s[4:5]
	v_mov_b32_e32 v13, 1.0
	s_cbranch_vccnz .LBB0_51
	v_mov_b32_e32 v13, v3
	v_lshl_add_u64 v[78:79], v[12:13], 2, s[58:59]
	global_load_dword v13, v[78:79], off offset:64 nt
.LBB0_51:
	v_or_b32_e32 v2, s7, v33
	v_lshlrev_b64 v[78:79], 14, v[2:3]
	v_lshl_add_u64 v[78:79], v[10:11], 0, v[78:79]
	global_load_dword v78, v[78:79], off nt
	s_waitcnt vmcnt(1)
	v_mul_f32_e32 v2, v77, v13
	v_add_u32_e32 v13, v15, v32
	s_and_b64 vcc, exec, s[4:5]
	ds_write_b32 v13, v2
	s_cbranch_vccnz .LBB0_53
	v_mov_b32_e32 v13, v3
	v_lshl_add_u64 v[76:77], v[12:13], 2, s[58:59]
	global_load_dword v76, v[76:77], off offset:72 nt
.LBB0_53:
	v_or_b32_e32 v2, s7, v35
	v_lshlrev_b64 v[80:81], 14, v[2:3]
	v_lshl_add_u64 v[80:81], v[10:11], 0, v[80:81]
	global_load_dword v77, v[80:81], off nt
	s_waitcnt vmcnt(1)
	v_mul_f32_e32 v2, v78, v76
	v_add_u32_e32 v13, v15, v34
	ds_write_b32 v13, v2
	v_mov_b32_e32 v76, 1.0
	s_and_b64 vcc, exec, s[4:5]
	v_mov_b32_e32 v13, 1.0
	s_cbranch_vccnz .LBB0_55
	v_mov_b32_e32 v13, v3
	v_lshl_add_u64 v[78:79], v[12:13], 2, s[58:59]
	global_load_dword v13, v[78:79], off offset:80 nt
.LBB0_55:
	v_or_b32_e32 v2, s7, v37
	v_lshlrev_b64 v[78:79], 14, v[2:3]
	v_lshl_add_u64 v[78:79], v[10:11], 0, v[78:79]
	global_load_dword v78, v[78:79], off nt
	s_waitcnt vmcnt(1)
	v_mul_f32_e32 v2, v77, v13
	v_add_u32_e32 v13, v15, v36
	s_and_b64 vcc, exec, s[4:5]
	ds_write_b32 v13, v2
	s_cbranch_vccnz .LBB0_57
	v_mov_b32_e32 v13, v3
	v_lshl_add_u64 v[76:77], v[12:13], 2, s[58:59]
	global_load_dword v76, v[76:77], off offset:88 nt
.LBB0_57:
	v_or_b32_e32 v2, s7, v39
	v_lshlrev_b64 v[80:81], 14, v[2:3]
	v_lshl_add_u64 v[80:81], v[10:11], 0, v[80:81]
	global_load_dword v77, v[80:81], off nt
	s_waitcnt vmcnt(1)
	v_mul_f32_e32 v2, v78, v76
	v_add_u32_e32 v13, v15, v38
	ds_write_b32 v13, v2
	v_mov_b32_e32 v76, 1.0
	s_and_b64 vcc, exec, s[4:5]
	v_mov_b32_e32 v13, 1.0
	s_cbranch_vccnz .LBB0_59
	v_mov_b32_e32 v13, v3
	v_lshl_add_u64 v[78:79], v[12:13], 2, s[58:59]
	global_load_dword v13, v[78:79], off offset:96 nt
.LBB0_59:
	v_or_b32_e32 v2, s7, v41
	v_lshlrev_b64 v[78:79], 14, v[2:3]
	v_lshl_add_u64 v[78:79], v[10:11], 0, v[78:79]
	global_load_dword v78, v[78:79], off nt
	s_waitcnt vmcnt(1)
	v_mul_f32_e32 v2, v77, v13
	v_add_u32_e32 v13, v15, v40
	s_and_b64 vcc, exec, s[4:5]
	ds_write_b32 v13, v2
	s_cbranch_vccnz .LBB0_61
	v_mov_b32_e32 v13, v3
	v_lshl_add_u64 v[76:77], v[12:13], 2, s[58:59]
	global_load_dword v76, v[76:77], off offset:104 nt
.LBB0_61:
	v_or_b32_e32 v2, s7, v43
	v_lshlrev_b64 v[80:81], 14, v[2:3]
	v_lshl_add_u64 v[80:81], v[10:11], 0, v[80:81]
	global_load_dword v77, v[80:81], off nt
	s_waitcnt vmcnt(1)
	v_mul_f32_e32 v2, v78, v76
	v_add_u32_e32 v13, v15, v42
	ds_write_b32 v13, v2
	v_mov_b32_e32 v76, 1.0
	s_and_b64 vcc, exec, s[4:5]
	v_mov_b32_e32 v13, 1.0
	s_cbranch_vccnz .LBB0_63
	v_mov_b32_e32 v13, v3
	v_lshl_add_u64 v[78:79], v[12:13], 2, s[58:59]
	global_load_dword v13, v[78:79], off offset:112 nt
.LBB0_63:
	v_or_b32_e32 v2, s7, v45
	v_lshlrev_b64 v[78:79], 14, v[2:3]
	v_lshl_add_u64 v[78:79], v[10:11], 0, v[78:79]
	global_load_dword v78, v[78:79], off nt
	s_waitcnt vmcnt(1)
	v_mul_f32_e32 v2, v77, v13
	v_add_u32_e32 v13, v15, v44
	s_and_b64 vcc, exec, s[4:5]
	ds_write_b32 v13, v2
	s_cbranch_vccnz .LBB0_65
	v_mov_b32_e32 v13, v3
	v_lshl_add_u64 v[76:77], v[12:13], 2, s[58:59]
	global_load_dword v76, v[76:77], off offset:120 nt
.LBB0_65:
	v_or_b32_e32 v2, s7, v47
	v_lshlrev_b64 v[80:81], 14, v[2:3]
	v_lshl_add_u64 v[80:81], v[10:11], 0, v[80:81]
	global_load_dword v77, v[80:81], off nt
	s_waitcnt vmcnt(1)
	v_mul_f32_e32 v2, v78, v76
	v_add_u32_e32 v13, v15, v46
	ds_write_b32 v13, v2
	v_mov_b32_e32 v76, 1.0
	s_and_b64 vcc, exec, s[4:5]
	v_mov_b32_e32 v13, 1.0
	s_cbranch_vccnz .LBB0_67
	v_mov_b32_e32 v13, v3
	v_lshl_add_u64 v[78:79], v[12:13], 2, s[58:59]
	global_load_dword v13, v[78:79], off offset:128 nt
.LBB0_67:
	v_or_b32_e32 v2, s7, v49
	v_lshlrev_b64 v[78:79], 14, v[2:3]
	v_lshl_add_u64 v[78:79], v[10:11], 0, v[78:79]
	global_load_dword v78, v[78:79], off nt
	s_waitcnt vmcnt(1)
	v_mul_f32_e32 v2, v77, v13
	v_add_u32_e32 v13, v15, v48
	s_and_b64 vcc, exec, s[4:5]
	ds_write_b32 v13, v2
	s_cbranch_vccnz .LBB0_69
	v_mov_b32_e32 v13, v3
	v_lshl_add_u64 v[76:77], v[12:13], 2, s[58:59]
	global_load_dword v76, v[76:77], off offset:136 nt
.LBB0_69:
	v_or_b32_e32 v2, s7, v51
	v_lshlrev_b64 v[80:81], 14, v[2:3]
	v_lshl_add_u64 v[80:81], v[10:11], 0, v[80:81]
	global_load_dword v77, v[80:81], off nt
	s_waitcnt vmcnt(1)
	v_mul_f32_e32 v2, v78, v76
	v_add_u32_e32 v13, v15, v50
	ds_write_b32 v13, v2
	v_mov_b32_e32 v76, 1.0
	s_and_b64 vcc, exec, s[4:5]
	v_mov_b32_e32 v13, 1.0
	s_cbranch_vccnz .LBB0_71
	v_mov_b32_e32 v13, v3
	v_lshl_add_u64 v[78:79], v[12:13], 2, s[58:59]
	global_load_dword v13, v[78:79], off offset:144 nt
.LBB0_71:
	v_or_b32_e32 v2, s7, v53
	v_lshlrev_b64 v[78:79], 14, v[2:3]
	v_lshl_add_u64 v[78:79], v[10:11], 0, v[78:79]
	global_load_dword v78, v[78:79], off nt
	s_waitcnt vmcnt(1)
	v_mul_f32_e32 v2, v77, v13
	v_add_u32_e32 v13, v15, v52
	s_and_b64 vcc, exec, s[4:5]
	ds_write_b32 v13, v2
	s_cbranch_vccnz .LBB0_73
	v_mov_b32_e32 v13, v3
	v_lshl_add_u64 v[76:77], v[12:13], 2, s[58:59]
	global_load_dword v76, v[76:77], off offset:152 nt
.LBB0_73:
	v_or_b32_e32 v2, s7, v55
	v_lshlrev_b64 v[80:81], 14, v[2:3]
	v_lshl_add_u64 v[80:81], v[10:11], 0, v[80:81]
	global_load_dword v77, v[80:81], off nt
	s_waitcnt vmcnt(1)
	v_mul_f32_e32 v2, v78, v76
	v_add_u32_e32 v13, v15, v54
	ds_write_b32 v13, v2
	v_mov_b32_e32 v76, 1.0
	s_and_b64 vcc, exec, s[4:5]
	v_mov_b32_e32 v13, 1.0
	s_cbranch_vccnz .LBB0_75
	v_mov_b32_e32 v13, v3
	v_lshl_add_u64 v[78:79], v[12:13], 2, s[58:59]
	global_load_dword v13, v[78:79], off offset:160 nt
.LBB0_75:
	v_or_b32_e32 v2, s7, v57
	v_lshlrev_b64 v[78:79], 14, v[2:3]
	v_lshl_add_u64 v[78:79], v[10:11], 0, v[78:79]
	global_load_dword v78, v[78:79], off nt
	s_waitcnt vmcnt(1)
	v_mul_f32_e32 v2, v77, v13
	v_add_u32_e32 v13, v15, v56
	s_and_b64 vcc, exec, s[4:5]
	ds_write_b32 v13, v2
	s_cbranch_vccnz .LBB0_77
	v_mov_b32_e32 v13, v3
	v_lshl_add_u64 v[76:77], v[12:13], 2, s[58:59]
	global_load_dword v76, v[76:77], off offset:168 nt
.LBB0_77:
	v_or_b32_e32 v2, s7, v59
	v_lshlrev_b64 v[80:81], 14, v[2:3]
	v_lshl_add_u64 v[80:81], v[10:11], 0, v[80:81]
	global_load_dword v79, v[80:81], off nt
	s_waitcnt vmcnt(1)
	v_mul_f32_e32 v2, v78, v76
	v_add_u32_e32 v76, v15, v58
	v_mov_b32_e32 v77, 1.0
	s_and_b64 vcc, exec, s[4:5]
	v_mov_b32_e32 v13, 1.0
	ds_write_b32 v76, v2
	s_cbranch_vccnz .LBB0_79
	v_mov_b32_e32 v13, v3
	v_lshl_add_u64 v[80:81], v[12:13], 2, s[58:59]
	global_load_dword v13, v[80:81], off offset:176 nt
.LBB0_79:
	v_or_b32_e32 v2, s7, v60
	v_lshlrev_b64 v[80:81], 14, v[2:3]
	v_lshl_add_u64 v[80:81], v[10:11], 0, v[80:81]
	global_load_dword v80, v[80:81], off nt
	s_waitcnt vmcnt(1)
	v_mul_f32_e32 v2, v79, v13
	s_and_b64 vcc, exec, s[4:5]
	ds_write_b32 v76, v2 offset:264
	s_cbranch_vccnz .LBB0_81
	v_mov_b32_e32 v13, v3
	v_lshl_add_u64 v[78:79], v[12:13], 2, s[58:59]
	global_load_dword v77, v[78:79], off offset:184 nt
.LBB0_81:
	v_or_b32_e32 v2, s7, v61
	v_lshlrev_b64 v[78:79], 14, v[2:3]
	v_lshl_add_u64 v[78:79], v[10:11], 0, v[78:79]
	global_load_dword v78, v[78:79], off nt
	s_waitcnt vmcnt(1)
	v_mul_f32_e32 v2, v80, v77
	v_mov_b32_e32 v77, 1.0
	s_and_b64 vcc, exec, s[4:5]
	v_mov_b32_e32 v13, 1.0
	ds_write_b32 v76, v2 offset:528
	s_cbranch_vccnz .LBB0_83
	v_mov_b32_e32 v13, v3
	v_lshl_add_u64 v[80:81], v[12:13], 2, s[58:59]
	global_load_dword v13, v[80:81], off offset:192 nt
.LBB0_83:
	v_or_b32_e32 v2, s7, v62
	v_lshlrev_b64 v[80:81], 14, v[2:3]
	v_lshl_add_u64 v[80:81], v[10:11], 0, v[80:81]
	global_load_dword v79, v[80:81], off nt
	s_waitcnt vmcnt(1)
	v_mul_f32_e32 v2, v78, v13
	s_and_b64 vcc, exec, s[4:5]
	ds_write_b32 v76, v2 offset:792
	s_cbranch_vccnz .LBB0_85
	v_mov_b32_e32 v13, v3
	v_lshl_add_u64 v[80:81], v[12:13], 2, s[58:59]
	global_load_dword v77, v[80:81], off offset:200 nt
.LBB0_85:
	v_or_b32_e32 v2, s7, v63
	v_lshlrev_b64 v[80:81], 14, v[2:3]
	v_lshl_add_u64 v[80:81], v[10:11], 0, v[80:81]
	global_load_dword v78, v[80:81], off nt
	s_waitcnt vmcnt(1)
	v_mul_f32_e32 v2, v79, v77
	v_mov_b32_e32 v77, 1.0
	s_and_b64 vcc, exec, s[4:5]
	v_mov_b32_e32 v13, 1.0
	ds_write_b32 v76, v2 offset:1056
	s_cbranch_vccnz .LBB0_87
	v_mov_b32_e32 v13, v3
	v_lshl_add_u64 v[80:81], v[12:13], 2, s[58:59]
	global_load_dword v13, v[80:81], off offset:208 nt
.LBB0_87:
	v_or_b32_e32 v2, s7, v64
	v_lshlrev_b64 v[80:81], 14, v[2:3]
	v_lshl_add_u64 v[80:81], v[10:11], 0, v[80:81]
	global_load_dword v79, v[80:81], off nt
	s_waitcnt vmcnt(1)
	v_mul_f32_e32 v2, v78, v13
	s_and_b64 vcc, exec, s[4:5]
	ds_write_b32 v76, v2 offset:1320
	s_cbranch_vccnz .LBB0_89
	v_mov_b32_e32 v13, v3
	v_lshl_add_u64 v[80:81], v[12:13], 2, s[58:59]
	global_load_dword v77, v[80:81], off offset:216 nt
.LBB0_89:
	v_or_b32_e32 v2, s7, v65
	v_lshlrev_b64 v[80:81], 14, v[2:3]
	v_lshl_add_u64 v[80:81], v[10:11], 0, v[80:81]
	global_load_dword v78, v[80:81], off nt
	s_waitcnt vmcnt(1)
	v_mul_f32_e32 v2, v79, v77
	v_mov_b32_e32 v77, 1.0
	s_and_b64 vcc, exec, s[4:5]
	v_mov_b32_e32 v13, 1.0
	ds_write_b32 v76, v2 offset:1584
	s_cbranch_vccnz .LBB0_91
	v_mov_b32_e32 v13, v3
	v_lshl_add_u64 v[80:81], v[12:13], 2, s[58:59]
	global_load_dword v13, v[80:81], off offset:224 nt
.LBB0_91:
	v_or_b32_e32 v2, s7, v66
	v_lshlrev_b64 v[80:81], 14, v[2:3]
	v_lshl_add_u64 v[80:81], v[10:11], 0, v[80:81]
	global_load_dword v79, v[80:81], off nt
	s_waitcnt vmcnt(1)
	v_mul_f32_e32 v2, v78, v13
	s_and_b64 vcc, exec, s[4:5]
	ds_write_b32 v76, v2 offset:1848
	s_cbranch_vccnz .LBB0_93
	v_mov_b32_e32 v13, v3
	v_lshl_add_u64 v[80:81], v[12:13], 2, s[58:59]
	global_load_dword v77, v[80:81], off offset:232 nt
.LBB0_93:
	v_or_b32_e32 v2, s7, v67
	v_lshlrev_b64 v[80:81], 14, v[2:3]
	v_lshl_add_u64 v[80:81], v[10:11], 0, v[80:81]
	global_load_dword v78, v[80:81], off nt
	s_waitcnt vmcnt(1)
	v_mul_f32_e32 v2, v79, v77
	s_and_b64 vcc, exec, s[4:5]
	ds_write_b32 v76, v2 offset:2112
	s_cbranch_vccnz .LBB0_95
	v_mov_b32_e32 v13, v3
	v_lshl_add_u64 v[80:81], v[12:13], 2, s[58:59]
	global_load_dword v13, v[80:81], off offset:240 nt
	s_branch .LBB0_96

.LBB0_96:
	v_or_b32_e32 v2, s7, v68
	v_lshlrev_b64 v[80:81], 14, v[2:3]
	v_lshl_add_u64 v[10:11], v[10:11], 0, v[80:81]
	global_load_dword v2, v[10:11], off nt
	s_waitcnt vmcnt(1)
	v_mul_f32_e32 v10, v78, v13
	s_and_b64 vcc, exec, s[12:13]
	ds_write_b32 v76, v10 offset:2376
	s_cbranch_vccz .LBB0_149
	v_mov_b32_e32 v13, v3
	v_lshl_add_u64 v[10:11], v[12:13], 2, s[58:59]
	global_load_dword v10, v[10:11], off offset:248 nt
	s_cbranch_execnz .LBB0_99

.LBB0_100:
	s_and_b64 vcc, exec, s[4:5]
	s_cbranch_vccz .LBB0_107
	s_add_i32 s4, s0, 0xba00
	s_and_b32 s5, s4, 0xffff
	s_mul_i32 s5, s5, 0xaaab
	s_lshr_b32 s6, s5, 22
	s_mul_i32 s5, s6, 0x60
	s_sub_i32 s4, s4, s5
	s_lshl_b32 s4, s4, 5
	s_and_b32 s29, s4, 0xffe0
	v_or_b32_e32 v2, s29, v1
	v_mul_u32_u24_e32 v10, 0x2aab, v2
	v_lshrrev_b32_e32 v10, 21, v10
	v_mul_lo_u16_e32 v10, 0xc0, v10
	v_sub_u16_e32 v10, v2, v10
	v_cmp_lt_u16_e32 vcc, s24, v10
	s_and_saveexec_b64 s[4:5], vcc
	v_add_u32_e32 v11, 0xffffff80, v10
	v_lshrrev_b32_e32 v11, 1, v11
	v_lshlrev_b32_e32 v12, 5, v10
	v_sub_u32_e32 v2, v2, v10
	v_and_b32_e32 v12, 32, v12
	v_add_u32_e32 v2, v2, v11
	v_add3_u32 v2, v2, v12, s25
	s_or_b64 exec, exec, s[4:5]
	s_lshl_b32 s4, s6, 6
	s_and_b32 s8, s4, 0xffc0
	v_cmp_lt_i32_e64 s[4:5], -1, v2
	v_lshl_add_u64 v[10:11], v[2:3], 2, s[60:61]
	v_mov_b32_e32 v2, 0
	v_or_b32_e32 v12, s8, v14
	s_and_saveexec_b64 s[6:7], s[4:5]
	s_cbranch_execz .LBB0_105
	v_mul_u32_u24_e32 v2, 0x3000, v12
	v_lshl_add_u64 v[76:77], v[10:11], 0, v[2:3]
	global_load_dword v2, v[76:77], off nt
.LBB0_105:
	s_or_b64 exec, exec, s[6:7]
	v_cndmask_b32_e64 v13, 0, 1, s[14:15]
	v_cmp_ne_u32_e64 s[6:7], 1, v13
	s_andn2_b64 vcc, exec, s[14:15]
	s_cbranch_vccnz .LBB0_150
	v_lshlrev_b32_e32 v12, 2, v12
	global_load_dword v12, v12, s[56:57] nt
	s_branch .LBB0_151

.LBB0_115:
	s_andn2_saveexec_b64 s[4:5], s[4:5]
	s_and_b32 s6, s8, 0xffffff80
	v_bfe_u32 v2, v2, 1, 6
	v_and_b32_e32 v10, 64, v75
	v_or3_b32 v2, v2, s6, v10
	s_or_b64 exec, exec, s[4:5]
	v_cmp_gt_i32_e32 vcc, 0, v2
	v_add_u32_e32 v12, v15, v16
	s_and_saveexec_b64 s[4:5], vcc
	s_xor_b64 s[4:5], exec, s[4:5]
	ds_write2_b32 v12, v3, v3 offset1:66
	s_or_saveexec_b64 s[6:7], s[4:5]
	s_lshl_b32 s4, s16, 6
	v_lshl_add_u64 v[10:11], v[2:3], 2, s[50:51]
	v_mov_b32_e32 v2, 0
	v_mov_b32_e32 v13, 0
	s_xor_b64 exec, exec, s[6:7]
	s_cbranch_execz .LBB0_121
	v_or_b32_e32 v2, s4, v14
	v_mad_i64_i32 v[76:77], s[16:17], v2, s28, v[10:11]
	v_or_b32_e32 v2, s4, v17
	v_mad_i64_i32 v[78:79], s[16:17], v2, s28, v[10:11]
	v_or_b32_e32 v2, s4, v19
	v_mad_i64_i32 v[80:81], s[16:17], v2, s28, v[10:11]
	v_or_b32_e32 v2, s4, v21
	v_mad_i64_i32 v[82:83], s[16:17], v2, s28, v[10:11]
	global_load_dword v76, v[76:77], off nt
	s_nop 0
	global_load_dword v77, v[78:79], off nt
	global_load_dword v2, v[80:81], off nt
	global_load_dword v13, v[82:83], off nt
	s_waitcnt vmcnt(2)
	ds_write2_b32 v12, v76, v77 offset1:66
.LBB0_121:
	s_or_b64 exec, exec, s[6:7]
	v_add_u32_e32 v12, v15, v20
	s_waitcnt vmcnt(0)
	ds_write2_b32 v12, v2, v13 offset1:66
	v_add_u32_e32 v2, v15, v24
	s_and_saveexec_b64 s[6:7], vcc
	s_xor_b64 s[6:7], exec, s[6:7]
	ds_write2_b32 v2, v3, v3 offset1:66
	s_or_saveexec_b64 s[6:7], s[6:7]
	v_mov_b32_e32 v12, 0
	v_mov_b32_e32 v13, 0
	s_xor_b64 exec, exec, s[6:7]
	s_cbranch_execz .LBB0_125
	v_or_b32_e32 v12, s4, v23
	v_or_b32_e32 v76, s4, v25
	v_mad_i64_i32 v[12:13], s[16:17], v12, s28, v[10:11]
	v_mad_i64_i32 v[76:77], s[16:17], v76, s28, v[10:11]
	v_or_b32_e32 v78, s4, v27
	v_or_b32_e32 v80, s4, v29
	v_mad_i64_i32 v[78:79], s[16:17], v78, s28, v[10:11]
	v_mad_i64_i32 v[80:81], s[16:17], v80, s28, v[10:11]
	global_load_dword v82, v[12:13], off nt
	s_nop 0
	global_load_dword v76, v[76:77], off nt
	s_nop 0
	global_load_dword v12, v[78:79], off nt
	global_load_dword v13, v[80:81], off nt
	s_waitcnt vmcnt(2)
	ds_write2_b32 v2, v82, v76 offset1:66
.LBB0_125:
	s_or_b64 exec, exec, s[6:7]
	v_add_u32_e32 v2, v15, v28
	s_waitcnt vmcnt(0)
	ds_write2_b32 v2, v12, v13 offset1:66
	v_add_u32_e32 v2, v15, v32
	s_and_saveexec_b64 s[6:7], vcc
	s_xor_b64 s[6:7], exec, s[6:7]
	ds_write2_b32 v2, v3, v3 offset1:66
	s_or_saveexec_b64 s[6:7], s[6:7]
	v_mov_b32_e32 v12, 0
	v_mov_b32_e32 v13, 0
	s_xor_b64 exec, exec, s[6:7]
	s_cbranch_execz .LBB0_129
	v_or_b32_e32 v12, s4, v31
	v_or_b32_e32 v76, s4, v33
	v_mad_i64_i32 v[12:13], s[16:17], v12, s28, v[10:11]
	v_mad_i64_i32 v[76:77], s[16:17], v76, s28, v[10:11]
	v_or_b32_e32 v78, s4, v35
	v_or_b32_e32 v80, s4, v37
	v_mad_i64_i32 v[78:79], s[16:17], v78, s28, v[10:11]
	v_mad_i64_i32 v[80:81], s[16:17], v80, s28, v[10:11]
	global_load_dword v82, v[12:13], off nt
	s_nop 0
	global_load_dword v76, v[76:77], off nt
	s_nop 0
	global_load_dword v12, v[78:79], off nt
	global_load_dword v13, v[80:81], off nt
	s_waitcnt vmcnt(2)
	ds_write2_b32 v2, v82, v76 offset1:66
.LBB0_129:
	s_or_b64 exec, exec, s[6:7]
	v_add_u32_e32 v2, v15, v36
	s_waitcnt vmcnt(0)
	ds_write2_b32 v2, v12, v13 offset1:66
	v_add_u32_e32 v2, v15, v40
	s_and_saveexec_b64 s[6:7], vcc
	s_xor_b64 s[6:7], exec, s[6:7]
	ds_write2_b32 v2, v3, v3 offset1:66
	s_or_saveexec_b64 s[6:7], s[6:7]
	v_mov_b32_e32 v12, 0
	v_mov_b32_e32 v13, 0
	s_xor_b64 exec, exec, s[6:7]
	s_cbranch_execz .LBB0_133
	v_or_b32_e32 v12, s4, v39
	v_or_b32_e32 v76, s4, v41
	v_mad_i64_i32 v[12:13], s[16:17], v12, s28, v[10:11]
	v_mad_i64_i32 v[76:77], s[16:17], v76, s28, v[10:11]
	v_or_b32_e32 v78, s4, v43
	v_or_b32_e32 v80, s4, v45
	v_mad_i64_i32 v[78:79], s[16:17], v78, s28, v[10:11]
	v_mad_i64_i32 v[80:81], s[16:17], v80, s28, v[10:11]
	global_load_dword v82, v[12:13], off nt
	s_nop 0
	global_load_dword v76, v[76:77], off nt
	s_nop 0
	global_load_dword v12, v[78:79], off nt
	global_load_dword v13, v[80:81], off nt
	s_waitcnt vmcnt(2)
	ds_write2_b32 v2, v82, v76 offset1:66
.LBB0_133:
	s_or_b64 exec, exec, s[6:7]
	v_add_u32_e32 v2, v15, v44
	s_waitcnt vmcnt(0)
	ds_write2_b32 v2, v12, v13 offset1:66
	v_add_u32_e32 v2, v15, v48
	s_and_saveexec_b64 s[6:7], vcc
	s_xor_b64 s[6:7], exec, s[6:7]
	ds_write2_b32 v2, v3, v3 offset1:66
	s_or_saveexec_b64 s[6:7], s[6:7]
	v_mov_b32_e32 v12, 0
	v_mov_b32_e32 v13, 0
	s_xor_b64 exec, exec, s[6:7]
	s_cbranch_execz .LBB0_137
	v_or_b32_e32 v12, s4, v47
	v_or_b32_e32 v76, s4, v49
	v_mad_i64_i32 v[12:13], s[16:17], v12, s28, v[10:11]
	v_mad_i64_i32 v[76:77], s[16:17], v76, s28, v[10:11]
	v_or_b32_e32 v78, s4, v51
	v_or_b32_e32 v80, s4, v53
	v_mad_i64_i32 v[78:79], s[16:17], v78, s28, v[10:11]
	v_mad_i64_i32 v[80:81], s[16:17], v80, s28, v[10:11]
	global_load_dword v82, v[12:13], off nt
	s_nop 0
	global_load_dword v76, v[76:77], off nt
	s_nop 0
	global_load_dword v12, v[78:79], off nt
	global_load_dword v13, v[80:81], off nt
	s_waitcnt vmcnt(2)
	ds_write2_b32 v2, v82, v76 offset1:66
.LBB0_137:
	s_or_b64 exec, exec, s[6:7]
	v_add_u32_e32 v2, v15, v52
	s_waitcnt vmcnt(0)
	ds_write2_b32 v2, v12, v13 offset1:66
	v_add_u32_e32 v2, v15, v56
	s_and_saveexec_b64 s[6:7], vcc
	s_xor_b64 s[6:7], exec, s[6:7]
	ds_write2_b32 v2, v3, v3 offset1:66
	s_or_saveexec_b64 s[6:7], s[6:7]
	v_mov_b32_e32 v12, 0
	v_mov_b32_e32 v13, 0
	s_xor_b64 exec, exec, s[6:7]
	s_cbranch_execz .LBB0_141
	v_or_b32_e32 v12, s4, v55
	v_or_b32_e32 v76, s4, v57
	v_mad_i64_i32 v[12:13], s[16:17], v12, s28, v[10:11]
	v_mad_i64_i32 v[76:77], s[16:17], v76, s28, v[10:11]
	v_or_b32_e32 v78, s4, v59
	v_or_b32_e32 v80, s4, v60
	v_mad_i64_i32 v[78:79], s[16:17], v78, s28, v[10:11]
	v_mad_i64_i32 v[80:81], s[16:17], v80, s28, v[10:11]
	global_load_dword v82, v[12:13], off nt
	s_nop 0
	global_load_dword v76, v[76:77], off nt
	s_nop 0
	global_load_dword v12, v[78:79], off nt
	global_load_dword v13, v[80:81], off nt
	s_waitcnt vmcnt(2)
	ds_write2_b32 v2, v82, v76 offset1:66
.LBB0_141:
	s_or_b64 exec, exec, s[6:7]
	v_add_u32_e32 v2, v15, v58
	s_waitcnt vmcnt(0)
	ds_write2_b32 v2, v12, v13 offset0:66 offset1:132
	v_add_u32_e32 v12, 0x200, v2
	s_and_saveexec_b64 s[6:7], vcc
	s_xor_b64 s[6:7], exec, s[6:7]
	ds_write2_b32 v12, v3, v3 offset0:70 offset1:136
	s_or_saveexec_b64 s[6:7], s[6:7]
	v_mov_b32_e32 v13, 0
	v_mov_b32_e32 v76, 0
	s_xor_b64 exec, exec, s[6:7]
	s_cbranch_execz .LBB0_145
	v_or_b32_e32 v13, s4, v61
	v_mad_i64_i32 v[76:77], s[16:17], v13, s28, v[10:11]
	v_or_b32_e32 v13, s4, v62
	v_mad_i64_i32 v[78:79], s[16:17], v13, s28, v[10:11]
	v_or_b32_e32 v13, s4, v63
	v_mad_i64_i32 v[80:81], s[16:17], v13, s28, v[10:11]
	v_or_b32_e32 v13, s4, v64
	v_mad_i64_i32 v[82:83], s[16:17], v13, s28, v[10:11]
	global_load_dword v77, v[76:77], off nt
	s_nop 0
	global_load_dword v78, v[78:79], off nt
	s_nop 0
	global_load_dword v13, v[80:81], off nt
	global_load_dword v76, v[82:83], off nt
	s_waitcnt vmcnt(2)
	ds_write2_b32 v12, v77, v78 offset0:70 offset1:136
.LBB0_145:
	s_or_b64 exec, exec, s[6:7]
	v_add_u32_e32 v12, 0x400, v2
	s_waitcnt vmcnt(0)
	ds_write2_b32 v12, v13, v76 offset0:74 offset1:140
	v_add_u32_e32 v12, 0x600, v2
	s_and_saveexec_b64 s[6:7], vcc
	s_xor_b64 s[6:7], exec, s[6:7]
	ds_write2_b32 v12, v3, v3 offset0:78 offset1:144
	s_or_saveexec_b64 s[6:7], s[6:7]
	v_mov_b32_e32 v13, 0
	v_mov_b32_e32 v76, 0
	s_xor_b64 exec, exec, s[6:7]
	s_cbranch_execz .LBB0_29
	v_or_b32_e32 v13, s4, v65
	v_mad_i64_i32 v[76:77], s[16:17], v13, s28, v[10:11]
	v_or_b32_e32 v13, s4, v66
	v_mad_i64_i32 v[78:79], s[16:17], v13, s28, v[10:11]
	v_or_b32_e32 v13, s4, v67
	v_mad_i64_i32 v[80:81], s[16:17], v13, s28, v[10:11]
	v_or_b32_e32 v13, s4, v68
	v_mad_i64_i32 v[10:11], s[16:17], v13, s28, v[10:11]
	global_load_dword v77, v[76:77], off nt
	s_nop 0
	global_load_dword v78, v[78:79], off nt
	s_nop 0
	global_load_dword v13, v[80:81], off nt
	global_load_dword v76, v[10:11], off nt
	s_waitcnt vmcnt(2)
	ds_write2_b32 v12, v77, v78 offset0:78 offset1:144
	s_branch .LBB0_29

.LBB0_151:
	s_waitcnt vmcnt(0)
	v_mul_f32_e32 v2, v2, v12
	v_add_u32_e32 v12, v15, v16
	ds_write_b32 v12, v2
	v_mov_b32_e32 v2, 0
	s_and_saveexec_b64 s[16:17], s[4:5]
	s_cbranch_execz .LBB0_153
	v_or_b32_e32 v2, s8, v17
	v_mul_u32_u24_e32 v2, 0x3000, v2
	v_lshl_add_u64 v[12:13], v[10:11], 0, v[2:3]
	global_load_dword v2, v[12:13], off nt
.LBB0_153:
	s_or_b64 exec, exec, s[16:17]
	s_and_b64 vcc, exec, s[6:7]
	v_add_lshl_u32 v12, v14, s8, 2
	s_cbranch_vccnz .LBB0_155
	global_load_dword v13, v12, s[56:57] offset:8 nt
	s_branch .LBB0_156

.LBB0_156:
	s_waitcnt vmcnt(0)
	v_mul_f32_e32 v2, v2, v13
	v_add_u32_e32 v13, v15, v18
	ds_write_b32 v13, v2
	v_mov_b32_e32 v2, 0
	s_and_saveexec_b64 s[16:17], s[4:5]
	s_cbranch_execz .LBB0_158
	v_or_b32_e32 v2, s8, v19
	v_mul_u32_u24_e32 v2, 0x3000, v2
	v_lshl_add_u64 v[76:77], v[10:11], 0, v[2:3]
	global_load_dword v2, v[76:77], off nt
.LBB0_158:
	s_or_b64 exec, exec, s[16:17]
	s_and_b64 vcc, exec, s[6:7]
	s_cbranch_vccnz .LBB0_160
	global_load_dword v13, v12, s[56:57] offset:16 nt
	s_branch .LBB0_161

.LBB0_161:
	s_waitcnt vmcnt(0)
	v_mul_f32_e32 v2, v2, v13
	v_add_u32_e32 v13, v15, v20
	ds_write_b32 v13, v2
	v_mov_b32_e32 v2, 0
	s_and_saveexec_b64 s[16:17], s[4:5]
	s_cbranch_execz .LBB0_163
	v_or_b32_e32 v2, s8, v21
	v_mul_u32_u24_e32 v2, 0x3000, v2
	v_lshl_add_u64 v[76:77], v[10:11], 0, v[2:3]
	global_load_dword v2, v[76:77], off nt
.LBB0_163:
	s_or_b64 exec, exec, s[16:17]
	s_and_b64 vcc, exec, s[6:7]
	s_cbranch_vccnz .LBB0_165
	global_load_dword v13, v12, s[56:57] offset:24 nt
	s_branch .LBB0_166

.LBB0_166:
	s_waitcnt vmcnt(0)
	v_mul_f32_e32 v2, v2, v13
	v_add_u32_e32 v13, v15, v22
	ds_write_b32 v13, v2
	v_mov_b32_e32 v2, 0
	s_and_saveexec_b64 s[16:17], s[4:5]
	s_cbranch_execz .LBB0_168
	v_or_b32_e32 v2, s8, v23
	v_mul_u32_u24_e32 v2, 0x3000, v2
	v_lshl_add_u64 v[76:77], v[10:11], 0, v[2:3]
	global_load_dword v2, v[76:77], off nt
.LBB0_168:
	s_or_b64 exec, exec, s[16:17]
	s_and_b64 vcc, exec, s[6:7]
	s_cbranch_vccnz .LBB0_170
	global_load_dword v13, v12, s[56:57] offset:32 nt
	s_branch .LBB0_171

.LBB0_171:
	s_waitcnt vmcnt(0)
	v_mul_f32_e32 v2, v2, v13
	v_add_u32_e32 v13, v15, v24
	ds_write_b32 v13, v2
	v_mov_b32_e32 v2, 0
	s_and_saveexec_b64 s[16:17], s[4:5]
	s_cbranch_execz .LBB0_173
	v_or_b32_e32 v2, s8, v25
	v_mul_u32_u24_e32 v2, 0x3000, v2
	v_lshl_add_u64 v[76:77], v[10:11], 0, v[2:3]
	global_load_dword v2, v[76:77], off nt
.LBB0_173:
	s_or_b64 exec, exec, s[16:17]
	s_and_b64 vcc, exec, s[6:7]
	s_cbranch_vccnz .LBB0_175
	global_load_dword v13, v12, s[56:57] offset:40 nt
	s_branch .LBB0_176

.LBB0_176:
	s_waitcnt vmcnt(0)
	v_mul_f32_e32 v2, v2, v13
	v_add_u32_e32 v13, v15, v26
	ds_write_b32 v13, v2
	v_mov_b32_e32 v2, 0
	s_and_saveexec_b64 s[16:17], s[4:5]
	s_cbranch_execz .LBB0_178
	v_or_b32_e32 v2, s8, v27
	v_mul_u32_u24_e32 v2, 0x3000, v2
	v_lshl_add_u64 v[76:77], v[10:11], 0, v[2:3]
	global_load_dword v2, v[76:77], off nt
.LBB0_178:
	s_or_b64 exec, exec, s[16:17]
	s_and_b64 vcc, exec, s[6:7]
	s_cbranch_vccnz .LBB0_180
	global_load_dword v13, v12, s[56:57] offset:48 nt
	s_branch .LBB0_181

.LBB0_181:
	s_waitcnt vmcnt(0)
	v_mul_f32_e32 v2, v2, v13
	v_add_u32_e32 v13, v15, v28
	ds_write_b32 v13, v2
	v_mov_b32_e32 v2, 0
	s_and_saveexec_b64 s[16:17], s[4:5]
	s_cbranch_execz .LBB0_183
	v_or_b32_e32 v2, s8, v29
	v_mul_u32_u24_e32 v2, 0x3000, v2
	v_lshl_add_u64 v[76:77], v[10:11], 0, v[2:3]
	global_load_dword v2, v[76:77], off nt
.LBB0_183:
	s_or_b64 exec, exec, s[16:17]
	s_and_b64 vcc, exec, s[6:7]
	s_cbranch_vccnz .LBB0_185
	global_load_dword v13, v12, s[56:57] offset:56 nt
	s_branch .LBB0_186

.LBB0_186:
	s_waitcnt vmcnt(0)
	v_mul_f32_e32 v2, v2, v13
	v_add_u32_e32 v13, v15, v30
	ds_write_b32 v13, v2
	v_mov_b32_e32 v2, 0
	s_and_saveexec_b64 s[16:17], s[4:5]
	s_cbranch_execz .LBB0_188
	v_or_b32_e32 v2, s8, v31
	v_mul_u32_u24_e32 v2, 0x3000, v2
	v_lshl_add_u64 v[76:77], v[10:11], 0, v[2:3]
	global_load_dword v2, v[76:77], off nt
.LBB0_188:
	s_or_b64 exec, exec, s[16:17]
	s_and_b64 vcc, exec, s[6:7]
	s_cbranch_vccnz .LBB0_190
	global_load_dword v13, v12, s[56:57] offset:64 nt
	s_branch .LBB0_191

.LBB0_191:
	s_waitcnt vmcnt(0)
	v_mul_f32_e32 v2, v2, v13
	v_add_u32_e32 v13, v15, v32
	ds_write_b32 v13, v2
	v_mov_b32_e32 v2, 0
	s_and_saveexec_b64 s[16:17], s[4:5]
	s_cbranch_execz .LBB0_193
	v_or_b32_e32 v2, s8, v33
	v_mul_u32_u24_e32 v2, 0x3000, v2
	v_lshl_add_u64 v[76:77], v[10:11], 0, v[2:3]
	global_load_dword v2, v[76:77], off nt
.LBB0_193:
	s_or_b64 exec, exec, s[16:17]
	s_and_b64 vcc, exec, s[6:7]
	s_cbranch_vccnz .LBB0_195
	global_load_dword v13, v12, s[56:57] offset:72 nt
	s_branch .LBB0_196

.LBB0_196:
	s_waitcnt vmcnt(0)
	v_mul_f32_e32 v2, v2, v13
	v_add_u32_e32 v13, v15, v34
	ds_write_b32 v13, v2
	v_mov_b32_e32 v2, 0
	s_and_saveexec_b64 s[16:17], s[4:5]
	s_cbranch_execz .LBB0_198
	v_or_b32_e32 v2, s8, v35
	v_mul_u32_u24_e32 v2, 0x3000, v2
	v_lshl_add_u64 v[76:77], v[10:11], 0, v[2:3]
	global_load_dword v2, v[76:77], off nt
.LBB0_198:
	s_or_b64 exec, exec, s[16:17]
	s_and_b64 vcc, exec, s[6:7]
	s_cbranch_vccnz .LBB0_200
	global_load_dword v13, v12, s[56:57] offset:80 nt
	s_branch .LBB0_201

.LBB0_201:
	s_waitcnt vmcnt(0)
	v_mul_f32_e32 v2, v2, v13
	v_add_u32_e32 v13, v15, v36
	ds_write_b32 v13, v2
	v_mov_b32_e32 v2, 0
	s_and_saveexec_b64 s[16:17], s[4:5]
	s_cbranch_execz .LBB0_203
	v_or_b32_e32 v2, s8, v37
	v_mul_u32_u24_e32 v2, 0x3000, v2
	v_lshl_add_u64 v[76:77], v[10:11], 0, v[2:3]
	global_load_dword v2, v[76:77], off nt
.LBB0_203:
	s_or_b64 exec, exec, s[16:17]
	s_and_b64 vcc, exec, s[6:7]
	s_cbranch_vccnz .LBB0_205
	global_load_dword v13, v12, s[56:57] offset:88 nt
	s_branch .LBB0_206

.LBB0_206:
	s_waitcnt vmcnt(0)
	v_mul_f32_e32 v2, v2, v13
	v_add_u32_e32 v13, v15, v38
	ds_write_b32 v13, v2
	v_mov_b32_e32 v2, 0
	s_and_saveexec_b64 s[16:17], s[4:5]
	s_cbranch_execz .LBB0_208
	v_or_b32_e32 v2, s8, v39
	v_mul_u32_u24_e32 v2, 0x3000, v2
	v_lshl_add_u64 v[76:77], v[10:11], 0, v[2:3]
	global_load_dword v2, v[76:77], off nt
.LBB0_208:
	s_or_b64 exec, exec, s[16:17]
	s_and_b64 vcc, exec, s[6:7]
	s_cbranch_vccnz .LBB0_210
	global_load_dword v13, v12, s[56:57] offset:96 nt
	s_branch .LBB0_211

.LBB0_211:
	s_waitcnt vmcnt(0)
	v_mul_f32_e32 v2, v2, v13
	v_add_u32_e32 v13, v15, v40
	ds_write_b32 v13, v2
	v_mov_b32_e32 v2, 0
	s_and_saveexec_b64 s[16:17], s[4:5]
	s_cbranch_execz .LBB0_213
	v_or_b32_e32 v2, s8, v41
	v_mul_u32_u24_e32 v2, 0x3000, v2
	v_lshl_add_u64 v[76:77], v[10:11], 0, v[2:3]
	global_load_dword v2, v[76:77], off nt
.LBB0_213:
	s_or_b64 exec, exec, s[16:17]
	s_and_b64 vcc, exec, s[6:7]
	s_cbranch_vccnz .LBB0_215
	global_load_dword v13, v12, s[56:57] offset:104 nt
	s_branch .LBB0_216

.LBB0_216:
	s_waitcnt vmcnt(0)
	v_mul_f32_e32 v2, v2, v13
	v_add_u32_e32 v13, v15, v42
	ds_write_b32 v13, v2
	v_mov_b32_e32 v2, 0
	s_and_saveexec_b64 s[16:17], s[4:5]
	s_cbranch_execz .LBB0_218
	v_or_b32_e32 v2, s8, v43
	v_mul_u32_u24_e32 v2, 0x3000, v2
	v_lshl_add_u64 v[76:77], v[10:11], 0, v[2:3]
	global_load_dword v2, v[76:77], off nt
.LBB0_218:
	s_or_b64 exec, exec, s[16:17]
	s_and_b64 vcc, exec, s[6:7]
	s_cbranch_vccnz .LBB0_220
	global_load_dword v13, v12, s[56:57] offset:112 nt
	s_branch .LBB0_221

.LBB0_221:
	s_waitcnt vmcnt(0)
	v_mul_f32_e32 v2, v2, v13
	v_add_u32_e32 v13, v15, v44
	ds_write_b32 v13, v2
	v_mov_b32_e32 v2, 0
	s_and_saveexec_b64 s[16:17], s[4:5]
	s_cbranch_execz .LBB0_223
	v_or_b32_e32 v2, s8, v45
	v_mul_u32_u24_e32 v2, 0x3000, v2
	v_lshl_add_u64 v[76:77], v[10:11], 0, v[2:3]
	global_load_dword v2, v[76:77], off nt
.LBB0_223:
	s_or_b64 exec, exec, s[16:17]
	s_and_b64 vcc, exec, s[6:7]
	s_cbranch_vccnz .LBB0_225
	global_load_dword v13, v12, s[56:57] offset:120 nt
	s_branch .LBB0_226

.LBB0_226:
	s_waitcnt vmcnt(0)
	v_mul_f32_e32 v2, v2, v13
	v_add_u32_e32 v13, v15, v46
	ds_write_b32 v13, v2
	v_mov_b32_e32 v2, 0
	s_and_saveexec_b64 s[16:17], s[4:5]
	s_cbranch_execz .LBB0_228
	v_or_b32_e32 v2, s8, v47
	v_mul_u32_u24_e32 v2, 0x3000, v2
	v_lshl_add_u64 v[76:77], v[10:11], 0, v[2:3]
	global_load_dword v2, v[76:77], off nt
.LBB0_228:
	s_or_b64 exec, exec, s[16:17]
	s_and_b64 vcc, exec, s[6:7]
	s_cbranch_vccnz .LBB0_230
	global_load_dword v13, v12, s[56:57] offset:128 nt
	s_branch .LBB0_231

.LBB0_231:
	s_waitcnt vmcnt(0)
	v_mul_f32_e32 v2, v2, v13
	v_add_u32_e32 v13, v15, v48
	ds_write_b32 v13, v2
	v_mov_b32_e32 v2, 0
	s_and_saveexec_b64 s[16:17], s[4:5]
	s_cbranch_execz .LBB0_233
	v_or_b32_e32 v2, s8, v49
	v_mul_u32_u24_e32 v2, 0x3000, v2
	v_lshl_add_u64 v[76:77], v[10:11], 0, v[2:3]
	global_load_dword v2, v[76:77], off nt
.LBB0_233:
	s_or_b64 exec, exec, s[16:17]
	s_and_b64 vcc, exec, s[6:7]
	s_cbranch_vccnz .LBB0_235
	global_load_dword v13, v12, s[56:57] offset:136 nt
	s_branch .LBB0_236

.LBB0_236:
	s_waitcnt vmcnt(0)
	v_mul_f32_e32 v2, v2, v13
	v_add_u32_e32 v13, v15, v50
	ds_write_b32 v13, v2
	v_mov_b32_e32 v2, 0
	s_and_saveexec_b64 s[16:17], s[4:5]
	s_cbranch_execz .LBB0_238
	v_or_b32_e32 v2, s8, v51
	v_mul_u32_u24_e32 v2, 0x3000, v2
	v_lshl_add_u64 v[76:77], v[10:11], 0, v[2:3]
	global_load_dword v2, v[76:77], off nt
.LBB0_238:
	s_or_b64 exec, exec, s[16:17]
	s_and_b64 vcc, exec, s[6:7]
	s_cbranch_vccnz .LBB0_240
	global_load_dword v13, v12, s[56:57] offset:144 nt
	s_branch .LBB0_241

.LBB0_241:
	s_waitcnt vmcnt(0)
	v_mul_f32_e32 v2, v2, v13
	v_add_u32_e32 v13, v15, v52
	ds_write_b32 v13, v2
	v_mov_b32_e32 v2, 0
	s_and_saveexec_b64 s[16:17], s[4:5]
	s_cbranch_execz .LBB0_243
	v_or_b32_e32 v2, s8, v53
	v_mul_u32_u24_e32 v2, 0x3000, v2
	v_lshl_add_u64 v[76:77], v[10:11], 0, v[2:3]
	global_load_dword v2, v[76:77], off nt
.LBB0_243:
	s_or_b64 exec, exec, s[16:17]
	s_and_b64 vcc, exec, s[6:7]
	s_cbranch_vccnz .LBB0_245
	global_load_dword v13, v12, s[56:57] offset:152 nt
	s_branch .LBB0_246

.LBB0_246:
	s_waitcnt vmcnt(0)
	v_mul_f32_e32 v2, v2, v13
	v_add_u32_e32 v13, v15, v54
	ds_write_b32 v13, v2
	v_mov_b32_e32 v2, 0
	s_and_saveexec_b64 s[16:17], s[4:5]
	s_cbranch_execz .LBB0_248
	v_or_b32_e32 v2, s8, v55
	v_mul_u32_u24_e32 v2, 0x3000, v2
	v_lshl_add_u64 v[76:77], v[10:11], 0, v[2:3]
	global_load_dword v2, v[76:77], off nt
.LBB0_248:
	s_or_b64 exec, exec, s[16:17]
	s_and_b64 vcc, exec, s[6:7]
	s_cbranch_vccnz .LBB0_250
	global_load_dword v13, v12, s[56:57] offset:160 nt
	s_branch .LBB0_251

.LBB0_251:
	s_waitcnt vmcnt(0)
	v_mul_f32_e32 v2, v2, v13
	v_add_u32_e32 v13, v15, v56
	ds_write_b32 v13, v2
	v_mov_b32_e32 v2, 0
	s_and_saveexec_b64 s[16:17], s[4:5]
	s_cbranch_execz .LBB0_253
	v_or_b32_e32 v2, s8, v57
	v_mul_u32_u24_e32 v2, 0x3000, v2
	v_lshl_add_u64 v[76:77], v[10:11], 0, v[2:3]
	global_load_dword v2, v[76:77], off nt
.LBB0_253:
	s_or_b64 exec, exec, s[16:17]
	s_and_b64 vcc, exec, s[6:7]
	s_cbranch_vccnz .LBB0_255
	global_load_dword v13, v12, s[56:57] offset:168 nt
	s_branch .LBB0_256

.LBB0_256:
	s_waitcnt vmcnt(0)
	v_mul_f32_e32 v2, v2, v13
	v_add_u32_e32 v13, v15, v58
	ds_write_b32 v13, v2
	v_mov_b32_e32 v2, 0
	s_and_saveexec_b64 s[16:17], s[4:5]
	s_cbranch_execz .LBB0_258
	v_or_b32_e32 v2, s8, v59
	v_mul_u32_u24_e32 v2, 0x3000, v2
	v_lshl_add_u64 v[76:77], v[10:11], 0, v[2:3]
	global_load_dword v2, v[76:77], off nt
.LBB0_258:
	s_or_b64 exec, exec, s[16:17]
	s_and_b64 vcc, exec, s[6:7]
	s_cbranch_vccnz .LBB0_260
	global_load_dword v76, v12, s[56:57] offset:176 nt
	s_branch .LBB0_261

.LBB0_261:
	s_waitcnt vmcnt(0)
	v_mul_f32_e32 v2, v2, v76
	ds_write_b32 v13, v2 offset:264
	v_mov_b32_e32 v2, 0
	s_and_saveexec_b64 s[16:17], s[4:5]
	s_cbranch_execz .LBB0_263
	v_or_b32_e32 v2, s8, v60
	v_mul_u32_u24_e32 v2, 0x3000, v2
	v_lshl_add_u64 v[76:77], v[10:11], 0, v[2:3]
	global_load_dword v2, v[76:77], off nt
.LBB0_263:
	s_or_b64 exec, exec, s[16:17]
	s_and_b64 vcc, exec, s[6:7]
	s_cbranch_vccnz .LBB0_265
	global_load_dword v76, v12, s[56:57] offset:184 nt
	s_branch .LBB0_266

.LBB0_266:
	s_waitcnt vmcnt(0)
	v_mul_f32_e32 v2, v2, v76
	ds_write_b32 v13, v2 offset:528
	v_mov_b32_e32 v2, 0
	s_and_saveexec_b64 s[16:17], s[4:5]
	s_cbranch_execz .LBB0_268
	v_or_b32_e32 v2, s8, v61
	v_mul_u32_u24_e32 v2, 0x3000, v2
	v_lshl_add_u64 v[76:77], v[10:11], 0, v[2:3]
	global_load_dword v2, v[76:77], off nt
.LBB0_268:
	s_or_b64 exec, exec, s[16:17]
	s_and_b64 vcc, exec, s[6:7]
	s_cbranch_vccnz .LBB0_270
	global_load_dword v76, v12, s[56:57] offset:192 nt
	s_branch .LBB0_271

.LBB0_271:
	s_waitcnt vmcnt(0)
	v_mul_f32_e32 v2, v2, v76
	ds_write_b32 v13, v2 offset:792
	v_mov_b32_e32 v2, 0
	s_and_saveexec_b64 s[16:17], s[4:5]
	s_cbranch_execz .LBB0_273
	v_or_b32_e32 v2, s8, v62
	v_mul_u32_u24_e32 v2, 0x3000, v2
	v_lshl_add_u64 v[76:77], v[10:11], 0, v[2:3]
	global_load_dword v2, v[76:77], off nt
.LBB0_273:
	s_or_b64 exec, exec, s[16:17]
	s_and_b64 vcc, exec, s[6:7]
	s_cbranch_vccnz .LBB0_275
	global_load_dword v76, v12, s[56:57] offset:200 nt
	s_branch .LBB0_276

.LBB0_276:
	s_waitcnt vmcnt(0)
	v_mul_f32_e32 v2, v2, v76
	ds_write_b32 v13, v2 offset:1056
	v_mov_b32_e32 v2, 0
	s_and_saveexec_b64 s[16:17], s[4:5]
	s_cbranch_execz .LBB0_278
	v_or_b32_e32 v2, s8, v63
	v_mul_u32_u24_e32 v2, 0x3000, v2
	v_lshl_add_u64 v[76:77], v[10:11], 0, v[2:3]
	global_load_dword v2, v[76:77], off nt
.LBB0_278:
	s_or_b64 exec, exec, s[16:17]
	s_and_b64 vcc, exec, s[6:7]
	s_cbranch_vccnz .LBB0_280
	global_load_dword v76, v12, s[56:57] offset:208 nt
	s_branch .LBB0_281

.LBB0_281:
	s_waitcnt vmcnt(0)
	v_mul_f32_e32 v2, v2, v76
	ds_write_b32 v13, v2 offset:1320
	v_mov_b32_e32 v2, 0
	s_and_saveexec_b64 s[16:17], s[4:5]
	s_cbranch_execz .LBB0_283
	v_or_b32_e32 v2, s8, v64
	v_mul_u32_u24_e32 v2, 0x3000, v2
	v_lshl_add_u64 v[76:77], v[10:11], 0, v[2:3]
	global_load_dword v2, v[76:77], off nt
.LBB0_283:
	s_or_b64 exec, exec, s[16:17]
	s_and_b64 vcc, exec, s[6:7]
	s_cbranch_vccnz .LBB0_285
	global_load_dword v76, v12, s[56:57] offset:216 nt
	s_branch .LBB0_286

.LBB0_286:
	s_waitcnt vmcnt(0)
	v_mul_f32_e32 v2, v2, v76
	ds_write_b32 v13, v2 offset:1584
	v_mov_b32_e32 v2, 0
	s_and_saveexec_b64 s[16:17], s[4:5]
	s_cbranch_execz .LBB0_288
	v_or_b32_e32 v2, s8, v65
	v_mul_u32_u24_e32 v2, 0x3000, v2
	v_lshl_add_u64 v[76:77], v[10:11], 0, v[2:3]
	global_load_dword v2, v[76:77], off nt
.LBB0_288:
	s_or_b64 exec, exec, s[16:17]
	s_and_b64 vcc, exec, s[6:7]
	s_cbranch_vccnz .LBB0_290
	global_load_dword v76, v12, s[56:57] offset:224 nt
	s_branch .LBB0_291

.LBB0_291:
	s_waitcnt vmcnt(0)
	v_mul_f32_e32 v2, v2, v76
	ds_write_b32 v13, v2 offset:1848
	v_mov_b32_e32 v2, 0
	s_and_saveexec_b64 s[16:17], s[4:5]
	s_cbranch_execz .LBB0_293
	v_or_b32_e32 v2, s8, v66
	v_mul_u32_u24_e32 v2, 0x3000, v2
	v_lshl_add_u64 v[76:77], v[10:11], 0, v[2:3]
	global_load_dword v2, v[76:77], off nt
.LBB0_293:
	s_or_b64 exec, exec, s[16:17]
	s_and_b64 vcc, exec, s[6:7]
	s_cbranch_vccnz .LBB0_295
	global_load_dword v76, v12, s[56:57] offset:232 nt
	s_branch .LBB0_296

.LBB0_296:
	s_waitcnt vmcnt(0)
	v_mul_f32_e32 v2, v2, v76
	ds_write_b32 v13, v2 offset:2112
	v_mov_b32_e32 v2, 0
	s_and_saveexec_b64 s[16:17], s[4:5]
	s_cbranch_execz .LBB0_298
	v_or_b32_e32 v2, s8, v67
	v_mul_u32_u24_e32 v2, 0x3000, v2
	v_lshl_add_u64 v[76:77], v[10:11], 0, v[2:3]
	global_load_dword v2, v[76:77], off nt
.LBB0_298:
	s_or_b64 exec, exec, s[16:17]
	s_and_b64 vcc, exec, s[6:7]
	s_cbranch_vccnz .LBB0_300
	global_load_dword v76, v12, s[56:57] offset:240 nt
	s_branch .LBB0_301

.LBB0_301:
	s_waitcnt vmcnt(0)
	v_mul_f32_e32 v2, v2, v76
	ds_write_b32 v13, v2 offset:2376
	v_mov_b32_e32 v2, 0
	s_and_saveexec_b64 s[16:17], s[4:5]
	s_cbranch_execz .LBB0_303
	v_or_b32_e32 v2, s8, v68
	v_mul_u32_u24_e32 v2, 0x3000, v2
	v_lshl_add_u64 v[10:11], v[10:11], 0, v[2:3]
	global_load_dword v2, v[10:11], off nt
.LBB0_303:
	s_or_b64 exec, exec, s[16:17]
	s_and_b64 vcc, exec, s[6:7]
	s_cbranch_vccnz .LBB0_305
	global_load_dword v10, v12, s[56:57] offset:248 nt
	s_branch .LBB0_306
